# 12c: head-group reduce-scatter via v_permlane32_swap / v_permlane16_swap / DPP row_ror:8 instead of cndmask + ds_bpermute
# baseline (speedup 1.0000x reference)
; DI void peer_v_phase(const Params& p) {
;     ...
;   auto gather = [&](PeerVRows& r, const int* e, int tok) {
; #pragma unroll
;     for (int i = 0; i < 16; ++i) r.v[i] = *(const u32x4*)(Vb + (size_t)e[i] * 128);
;     const float4* wp = (const float4*)(W + (size_t)tok * 128 + 16 * q);
; #pragma unroll
;     for (int j = 0; j < 4; ++j) r.w[j] = wp[j];
;   };
;   auto compute = [&](const PeerVRows& r, int tok) {
;     f32x2 o2[8];
; #pragma unroll
;     for (int k = 0; k < 8; ++k) { o2[k][0] = 0.f; o2[k][1] = 0.f; }
; #pragma unroll
;     for (int i = 0; i < 16; ++i) {
;       const float wi = (i & 3) == 0 ? r.w[i >> 2].x : (i & 3) == 1 ? r.w[i >> 2].y : (i & 3) == 2 ? r.w[i >> 2].z : r.w[i >> 2].w;
;       const f32x2 w2 = {wi, wi};
; #pragma unroll
;       for (int j = 0; j < 4; ++j) {
;         const f32x2 lo = __builtin_amdgcn_cvt_pk_f32_fp8((int)r.v[i][j], false);
;         const f32x2 hi = __builtin_amdgcn_cvt_pk_f32_fp8((int)r.v[i][j], true);
;         o2[2 * j] = __builtin_elementwise_fma(lo, w2, o2[2 * j]);
;         o2[2 * j + 1] = __builtin_elementwise_fma(hi, w2, o2[2 * j + 1]);
;       }
;     }
;     ...
;   for (int k = 0; k < n; k += 2) {
;     peer_load_e(ea, EID, tokof(k + 2), q);
;     gather(gb, eb, tokof(k + 1));
;     __builtin_amdgcn_sched_barrier(0);
;     compute(ga, tokof(k));
.LBB0_1477:
	s_add_i32 s19, s1, -1
	v_min_i32_e32 v60, s19, v195
	s_waitcnt lgkmcnt(0)
	v_mad_u64_u32 v[60:61], s[8:9], v60, s18, v[194:195]
	v_ashrrev_i32_e32 v61, 31, v60
	v_lshlrev_b64 v[208:209], 9, v[60:61]
	v_lshl_add_u64 v[60:61], v[198:199], 0, v[208:209]
	s_add_i32 s16, s1, -2
	global_load_dwordx4 v[172:175], v[60:61], off offset:48
	global_load_dwordx4 v[176:179], v[60:61], off offset:32
	global_load_dwordx4 v[184:187], v[60:61], off offset:16
	global_load_dwordx4 v[188:191], v[60:61], off
	v_min_i32_e32 v60, s16, v195
	v_mad_u64_u32 v[206:207], s[8:9], v60, s18, v[194:195]
	s_waitcnt vmcnt(4)
	v_ashrrev_i32_e32 v61, 31, v132
	v_mov_b32_e32 v60, v132
	v_ashrrev_i32_e32 v63, 31, v133
	v_mov_b32_e32 v62, v133
	v_lshlrev_b64 v[60:61], 7, v[60:61]
	v_lshlrev_b64 v[62:63], 7, v[62:63]
	v_lshl_add_u64 v[60:61], v[196:197], 0, v[60:61]
	v_lshl_add_u64 v[62:63], v[196:197], 0, v[62:63]
	global_load_dwordx4 v[168:171], v[60:61], off
	global_load_dwordx4 v[164:167], v[62:63], off
	v_ashrrev_i32_e32 v61, 31, v134
	v_mov_b32_e32 v60, v134
	v_ashrrev_i32_e32 v63, 31, v135
	v_mov_b32_e32 v62, v135
	v_lshlrev_b64 v[60:61], 7, v[60:61]
	v_lshlrev_b64 v[62:63], 7, v[62:63]
	v_lshl_add_u64 v[60:61], v[196:197], 0, v[60:61]
	v_lshl_add_u64 v[62:63], v[196:197], 0, v[62:63]
	global_load_dwordx4 v[160:163], v[60:61], off
	global_load_dwordx4 v[152:155], v[62:63], off
	v_ashrrev_i32_e32 v61, 31, v116
	v_mov_b32_e32 v60, v116
	v_ashrrev_i32_e32 v63, 31, v117
	v_mov_b32_e32 v62, v117
	v_lshlrev_b64 v[60:61], 7, v[60:61]
	v_lshlrev_b64 v[62:63], 7, v[62:63]
	v_lshl_add_u64 v[60:61], v[196:197], 0, v[60:61]
	v_lshl_add_u64 v[62:63], v[196:197], 0, v[62:63]
	global_load_dwordx4 v[148:151], v[60:61], off
	global_load_dwordx4 v[144:147], v[62:63], off
	v_ashrrev_i32_e32 v61, 31, v118
	v_mov_b32_e32 v60, v118
	v_ashrrev_i32_e32 v63, 31, v119
	v_mov_b32_e32 v62, v119
	v_lshlrev_b64 v[60:61], 7, v[60:61]
	v_lshlrev_b64 v[62:63], 7, v[62:63]
	v_lshl_add_u64 v[60:61], v[196:197], 0, v[60:61]
	v_lshl_add_u64 v[62:63], v[196:197], 0, v[62:63]
	global_load_dwordx4 v[140:143], v[60:61], off
	global_load_dwordx4 v[136:139], v[62:63], off
	v_ashrrev_i32_e32 v61, 31, v108
	v_mov_b32_e32 v60, v108
	v_ashrrev_i32_e32 v63, 31, v109
	v_mov_b32_e32 v62, v109
	v_lshlrev_b64 v[60:61], 7, v[60:61]
	v_lshlrev_b64 v[62:63], 7, v[62:63]
	v_lshl_add_u64 v[60:61], v[196:197], 0, v[60:61]
	v_lshl_add_u64 v[62:63], v[196:197], 0, v[62:63]
	global_load_dwordx4 v[128:131], v[60:61], off
	global_load_dwordx4 v[120:123], v[62:63], off
	v_ashrrev_i32_e32 v61, 31, v110
	v_mov_b32_e32 v60, v110
	v_ashrrev_i32_e32 v63, 31, v111
	v_mov_b32_e32 v62, v111
	v_lshlrev_b64 v[60:61], 7, v[60:61]
	v_lshlrev_b64 v[62:63], 7, v[62:63]
	v_lshl_add_u64 v[60:61], v[196:197], 0, v[60:61]
	v_lshl_add_u64 v[62:63], v[196:197], 0, v[62:63]
	global_load_dwordx4 v[112:115], v[60:61], off
	global_load_dwordx4 v[104:107], v[62:63], off
	v_ashrrev_i32_e32 v61, 31, v96
	v_mov_b32_e32 v60, v96
	v_ashrrev_i32_e32 v63, 31, v97
	v_mov_b32_e32 v62, v97
	v_lshlrev_b64 v[60:61], 7, v[60:61]
	v_lshlrev_b64 v[62:63], 7, v[62:63]
	v_lshl_add_u64 v[60:61], v[196:197], 0, v[60:61]
	v_lshl_add_u64 v[62:63], v[196:197], 0, v[62:63]
	global_load_dwordx4 v[100:103], v[60:61], off
	global_load_dwordx4 v[92:95], v[62:63], off
	v_ashrrev_i32_e32 v61, 31, v98
	v_mov_b32_e32 v60, v98
	v_ashrrev_i32_e32 v63, 31, v99
	v_mov_b32_e32 v62, v99
	v_ashrrev_i32_e32 v207, 31, v206
	v_lshlrev_b64 v[60:61], 7, v[60:61]
	v_lshlrev_b64 v[62:63], 7, v[62:63]
	v_lshlrev_b64 v[72:73], 9, v[206:207]
	v_lshl_add_u64 v[60:61], v[196:197], 0, v[60:61]
	v_lshl_add_u64 v[62:63], v[196:197], 0, v[62:63]
	v_lshl_add_u64 v[96:97], v[200:201], 0, v[72:73]
	global_load_dwordx4 v[68:71], v[60:61], off
	s_nop 0
	global_load_dwordx4 v[60:63], v[62:63], off
	s_nop 0
	global_load_dwordx4 v[72:75], v[96:97], off offset:48
	global_load_dwordx4 v[124:127], v[96:97], off offset:32
	global_load_dwordx4 v[156:159], v[96:97], off offset:16
	global_load_dwordx4 v[180:183], v[96:97], off
	v_cvt_pk_f32_fp8_e32 v[96:97], v88
	v_cvt_pk_f32_fp8_sdwa v[98:99], v88 src0_sel:WORD_1
	v_cvt_pk_f32_fp8_e32 v[108:109], v89
	v_cvt_pk_f32_fp8_sdwa v[88:89], v89 src0_sel:WORD_1
	v_cvt_pk_f32_fp8_e32 v[132:133], v84
	v_cvt_pk_f32_fp8_sdwa v[134:135], v84 src0_sel:WORD_1
	v_cvt_pk_f32_fp8_e32 v[216:217], v85
	v_cvt_pk_f32_fp8_sdwa v[84:85], v85 src0_sel:WORD_1
	v_pk_fma_f32 v[96:97], v[96:97], v[52:53], 0 op_sel_hi:[1,0,0]
	v_pk_fma_f32 v[98:99], v[98:99], v[52:53], 0 op_sel_hi:[1,0,0]
	v_pk_fma_f32 v[88:89], v[88:89], v[52:53], 0 op_sel_hi:[1,0,0]
	v_cvt_pk_f32_fp8_e32 v[110:111], v90
	v_cvt_pk_f32_fp8_sdwa v[116:117], v90 src0_sel:WORD_1
	v_cvt_pk_f32_fp8_e32 v[118:119], v91
	v_cvt_pk_f32_fp8_sdwa v[90:91], v91 src0_sel:WORD_1
	v_pk_fma_f32 v[96:97], v[132:133], v[52:53], v[96:97] op_sel:[0,1,0]
	v_pk_fma_f32 v[98:99], v[134:135], v[52:53], v[98:99] op_sel:[0,1,0]
	v_pk_fma_f32 v[84:85], v[84:85], v[52:53], v[88:89] op_sel:[0,1,0]
	v_cvt_pk_f32_fp8_e32 v[88:89], v86
	v_cvt_pk_f32_fp8_sdwa v[132:133], v86 src0_sel:WORD_1
	v_cvt_pk_f32_fp8_e32 v[134:135], v87
	v_cvt_pk_f32_fp8_sdwa v[86:87], v87 src0_sel:WORD_1
	v_pk_fma_f32 v[108:109], v[108:109], v[52:53], 0 op_sel_hi:[1,0,0]
	v_pk_fma_f32 v[110:111], v[110:111], v[52:53], 0 op_sel_hi:[1,0,0]
	v_pk_fma_f32 v[116:117], v[116:117], v[52:53], 0 op_sel_hi:[1,0,0]
	v_pk_fma_f32 v[118:119], v[118:119], v[52:53], 0 op_sel_hi:[1,0,0]
	v_pk_fma_f32 v[90:91], v[90:91], v[52:53], 0 op_sel_hi:[1,0,0]
	v_pk_fma_f32 v[108:109], v[216:217], v[52:53], v[108:109] op_sel:[0,1,0]
	v_pk_fma_f32 v[88:89], v[88:89], v[52:53], v[110:111] op_sel:[0,1,0]
; DI void peer_v_phase(const Params& p) {
;     ...
; #pragma unroll
;     for (int i = 0; i < 16; ++i) {
;       const float wi = (i & 3) == 0 ? r.w[i >> 2].x : (i & 3) == 1 ? r.w[i >> 2].y : (i & 3) == 2 ? r.w[i >> 2].z : r.w[i >> 2].w;
;       const f32x2 w2 = {wi, wi};
; #pragma unroll
;       for (int j = 0; j < 4; ++j) {
;         const f32x2 lo = __builtin_amdgcn_cvt_pk_f32_fp8((int)r.v[i][j], false);
;         const f32x2 hi = __builtin_amdgcn_cvt_pk_f32_fp8((int)r.v[i][j], true);
;         o2[2 * j] = __builtin_elementwise_fma(lo, w2, o2[2 * j]);
;         o2[2 * j + 1] = __builtin_elementwise_fma(hi, w2, o2[2 * j + 1]);
;       }
;     }
	v_pk_fma_f32 v[110:111], v[132:133], v[52:53], v[116:117] op_sel:[0,1,0]
	v_pk_fma_f32 v[116:117], v[134:135], v[52:53], v[118:119] op_sel:[0,1,0]
	v_pk_fma_f32 v[52:53], v[86:87], v[52:53], v[90:91] op_sel:[0,1,0]
	v_cvt_pk_f32_fp8_e32 v[86:87], v80
	v_cvt_pk_f32_fp8_sdwa v[90:91], v80 src0_sel:WORD_1
	v_cvt_pk_f32_fp8_e32 v[118:119], v81
	v_cvt_pk_f32_fp8_sdwa v[80:81], v81 src0_sel:WORD_1
	v_pk_fma_f32 v[86:87], v[86:87], v[54:55], v[96:97] op_sel_hi:[1,0,1]
	v_pk_fma_f32 v[90:91], v[90:91], v[54:55], v[98:99] op_sel_hi:[1,0,1]
	v_pk_fma_f32 v[96:97], v[118:119], v[54:55], v[108:109] op_sel_hi:[1,0,1]
	v_pk_fma_f32 v[80:81], v[80:81], v[54:55], v[84:85] op_sel_hi:[1,0,1]
	v_cvt_pk_f32_fp8_e32 v[84:85], v82
	v_cvt_pk_f32_fp8_sdwa v[98:99], v82 src0_sel:WORD_1
	v_cvt_pk_f32_fp8_e32 v[108:109], v83
	v_cvt_pk_f32_fp8_sdwa v[82:83], v83 src0_sel:WORD_1
	v_pk_fma_f32 v[84:85], v[84:85], v[54:55], v[88:89] op_sel_hi:[1,0,1]
	v_pk_fma_f32 v[88:89], v[98:99], v[54:55], v[110:111] op_sel_hi:[1,0,1]
	v_pk_fma_f32 v[98:99], v[108:109], v[54:55], v[116:117] op_sel_hi:[1,0,1]
	v_pk_fma_f32 v[52:53], v[82:83], v[54:55], v[52:53] op_sel_hi:[1,0,1]
	v_cvt_pk_f32_fp8_e32 v[82:83], v76
	v_cvt_pk_f32_fp8_sdwa v[108:109], v76 src0_sel:WORD_1
	v_cvt_pk_f32_fp8_e32 v[110:111], v77
	v_cvt_pk_f32_fp8_sdwa v[76:77], v77 src0_sel:WORD_1
	v_pk_fma_f32 v[82:83], v[82:83], v[54:55], v[86:87] op_sel:[0,1,0]
	v_pk_fma_f32 v[86:87], v[108:109], v[54:55], v[90:91] op_sel:[0,1,0]
	v_pk_fma_f32 v[90:91], v[110:111], v[54:55], v[96:97] op_sel:[0,1,0]
	v_pk_fma_f32 v[76:77], v[76:77], v[54:55], v[80:81] op_sel:[0,1,0]
	v_cvt_pk_f32_fp8_e32 v[80:81], v78
	v_cvt_pk_f32_fp8_sdwa v[96:97], v78 src0_sel:WORD_1
	v_cvt_pk_f32_fp8_e32 v[108:109], v79
	v_cvt_pk_f32_fp8_sdwa v[78:79], v79 src0_sel:WORD_1
	v_pk_fma_f32 v[80:81], v[80:81], v[54:55], v[84:85] op_sel:[0,1,0]
	v_pk_fma_f32 v[84:85], v[96:97], v[54:55], v[88:89] op_sel:[0,1,0]
	v_pk_fma_f32 v[88:89], v[108:109], v[54:55], v[98:99] op_sel:[0,1,0]
	v_pk_fma_f32 v[52:53], v[78:79], v[54:55], v[52:53] op_sel:[0,1,0]
	v_cvt_pk_f32_fp8_e32 v[54:55], v64
	v_cvt_pk_f32_fp8_sdwa v[78:79], v64 src0_sel:WORD_1
	v_cvt_pk_f32_fp8_e32 v[96:97], v65
	v_cvt_pk_f32_fp8_sdwa v[64:65], v65 src0_sel:WORD_1
	v_pk_fma_f32 v[54:55], v[54:55], v[28:29], v[82:83] op_sel_hi:[1,0,1]
	v_pk_fma_f32 v[78:79], v[78:79], v[28:29], v[86:87] op_sel_hi:[1,0,1]
	v_pk_fma_f32 v[82:83], v[96:97], v[28:29], v[90:91] op_sel_hi:[1,0,1]
	v_pk_fma_f32 v[64:65], v[64:65], v[28:29], v[76:77] op_sel_hi:[1,0,1]
	v_cvt_pk_f32_fp8_e32 v[76:77], v66
	v_cvt_pk_f32_fp8_sdwa v[86:87], v66 src0_sel:WORD_1
	v_cvt_pk_f32_fp8_e32 v[90:91], v67
	v_cvt_pk_f32_fp8_sdwa v[66:67], v67 src0_sel:WORD_1
	v_pk_fma_f32 v[76:77], v[76:77], v[28:29], v[80:81] op_sel_hi:[1,0,1]
	v_pk_fma_f32 v[80:81], v[86:87], v[28:29], v[84:85] op_sel_hi:[1,0,1]
	v_pk_fma_f32 v[84:85], v[90:91], v[28:29], v[88:89] op_sel_hi:[1,0,1]
	v_pk_fma_f32 v[52:53], v[66:67], v[28:29], v[52:53] op_sel_hi:[1,0,1]
	v_cvt_pk_f32_fp8_e32 v[66:67], v56
	v_cvt_pk_f32_fp8_sdwa v[86:87], v56 src0_sel:WORD_1
	v_cvt_pk_f32_fp8_e32 v[88:89], v57
	v_cvt_pk_f32_fp8_sdwa v[56:57], v57 src0_sel:WORD_1
	v_pk_fma_f32 v[54:55], v[66:67], v[28:29], v[54:55] op_sel:[0,1,0]
	v_pk_fma_f32 v[66:67], v[86:87], v[28:29], v[78:79] op_sel:[0,1,0]
	v_pk_fma_f32 v[78:79], v[88:89], v[28:29], v[82:83] op_sel:[0,1,0]
	v_pk_fma_f32 v[56:57], v[56:57], v[28:29], v[64:65] op_sel:[0,1,0]
	v_cvt_pk_f32_fp8_e32 v[64:65], v58
	v_cvt_pk_f32_fp8_sdwa v[82:83], v58 src0_sel:WORD_1
	v_cvt_pk_f32_fp8_e32 v[86:87], v59
	v_cvt_pk_f32_fp8_sdwa v[58:59], v59 src0_sel:WORD_1
	v_pk_fma_f32 v[64:65], v[64:65], v[28:29], v[76:77] op_sel:[0,1,0]
	v_pk_fma_f32 v[76:77], v[82:83], v[28:29], v[80:81] op_sel:[0,1,0]
	v_pk_fma_f32 v[80:81], v[86:87], v[28:29], v[84:85] op_sel:[0,1,0]
	v_pk_fma_f32 v[28:29], v[58:59], v[28:29], v[52:53] op_sel:[0,1,0]
	v_cvt_pk_f32_fp8_e32 v[52:53], v48
	v_cvt_pk_f32_fp8_sdwa v[58:59], v48 src0_sel:WORD_1
	v_cvt_pk_f32_fp8_e32 v[82:83], v49
	v_cvt_pk_f32_fp8_sdwa v[48:49], v49 src0_sel:WORD_1
	v_pk_fma_f32 v[52:53], v[52:53], v[30:31], v[54:55] op_sel_hi:[1,0,1]
	v_pk_fma_f32 v[54:55], v[58:59], v[30:31], v[66:67] op_sel_hi:[1,0,1]
	v_pk_fma_f32 v[58:59], v[82:83], v[30:31], v[78:79] op_sel_hi:[1,0,1]
	v_pk_fma_f32 v[48:49], v[48:49], v[30:31], v[56:57] op_sel_hi:[1,0,1]
	v_cvt_pk_f32_fp8_e32 v[56:57], v50
	v_cvt_pk_f32_fp8_sdwa v[66:67], v50 src0_sel:WORD_1
	v_cvt_pk_f32_fp8_e32 v[78:79], v51
	v_cvt_pk_f32_fp8_sdwa v[50:51], v51 src0_sel:WORD_1
	v_pk_fma_f32 v[56:57], v[56:57], v[30:31], v[64:65] op_sel_hi:[1,0,1]
	v_pk_fma_f32 v[64:65], v[66:67], v[30:31], v[76:77] op_sel_hi:[1,0,1]
	v_pk_fma_f32 v[66:67], v[78:79], v[30:31], v[80:81] op_sel_hi:[1,0,1]
	v_pk_fma_f32 v[28:29], v[50:51], v[30:31], v[28:29] op_sel_hi:[1,0,1]
	v_cvt_pk_f32_fp8_e32 v[50:51], v44
	v_cvt_pk_f32_fp8_sdwa v[76:77], v44 src0_sel:WORD_1
	v_cvt_pk_f32_fp8_e32 v[78:79], v45
	v_cvt_pk_f32_fp8_sdwa v[44:45], v45 src0_sel:WORD_1
	v_pk_fma_f32 v[50:51], v[50:51], v[30:31], v[52:53] op_sel:[0,1,0]
	v_pk_fma_f32 v[52:53], v[76:77], v[30:31], v[54:55] op_sel:[0,1,0]
	v_pk_fma_f32 v[54:55], v[78:79], v[30:31], v[58:59] op_sel:[0,1,0]
	v_pk_fma_f32 v[44:45], v[44:45], v[30:31], v[48:49] op_sel:[0,1,0]
	v_cvt_pk_f32_fp8_e32 v[48:49], v46
	v_cvt_pk_f32_fp8_sdwa v[58:59], v46 src0_sel:WORD_1
	v_cvt_pk_f32_fp8_e32 v[76:77], v47
	v_cvt_pk_f32_fp8_sdwa v[46:47], v47 src0_sel:WORD_1
	v_pk_fma_f32 v[48:49], v[48:49], v[30:31], v[56:57] op_sel:[0,1,0]
	v_pk_fma_f32 v[56:57], v[58:59], v[30:31], v[64:65] op_sel:[0,1,0]
	v_pk_fma_f32 v[58:59], v[76:77], v[30:31], v[66:67] op_sel:[0,1,0]
; DI void peer_v_phase(const Params& p) {
;     ...
; #pragma unroll
;     for (int i = 0; i < 16; ++i) {
;       const float wi = (i & 3) == 0 ? r.w[i >> 2].x : (i & 3) == 1 ? r.w[i >> 2].y : (i & 3) == 2 ? r.w[i >> 2].z : r.w[i >> 2].w;
;       const f32x2 w2 = {wi, wi};
; #pragma unroll
;       for (int j = 0; j < 4; ++j) {
;         const f32x2 lo = __builtin_amdgcn_cvt_pk_f32_fp8((int)r.v[i][j], false);
;         const f32x2 hi = __builtin_amdgcn_cvt_pk_f32_fp8((int)r.v[i][j], true);
;         o2[2 * j] = __builtin_elementwise_fma(lo, w2, o2[2 * j]);
;         o2[2 * j + 1] = __builtin_elementwise_fma(hi, w2, o2[2 * j + 1]);
;       }
;     }
;     ...
;     float* xr = p.out + (size_t)tok * 1024 + 128 * g + 16 * s + 2 * q;
;     float2 y = *(const float2*)xr;
	v_pk_fma_f32 v[28:29], v[46:47], v[30:31], v[28:29] op_sel:[0,1,0]
	v_cvt_pk_f32_fp8_e32 v[30:31], v40
	v_cvt_pk_f32_fp8_sdwa v[46:47], v40 src0_sel:WORD_1
	v_cvt_pk_f32_fp8_e32 v[64:65], v41
	v_cvt_pk_f32_fp8_sdwa v[40:41], v41 src0_sel:WORD_1
	v_pk_fma_f32 v[30:31], v[30:31], v[12:13], v[50:51] op_sel_hi:[1,0,1]
	v_pk_fma_f32 v[46:47], v[46:47], v[12:13], v[52:53] op_sel_hi:[1,0,1]
	v_pk_fma_f32 v[50:51], v[64:65], v[12:13], v[54:55] op_sel_hi:[1,0,1]
	v_pk_fma_f32 v[40:41], v[40:41], v[12:13], v[44:45] op_sel_hi:[1,0,1]
	v_cvt_pk_f32_fp8_e32 v[44:45], v42
	v_cvt_pk_f32_fp8_sdwa v[52:53], v42 src0_sel:WORD_1
	v_cvt_pk_f32_fp8_e32 v[54:55], v43
	v_cvt_pk_f32_fp8_sdwa v[42:43], v43 src0_sel:WORD_1
	v_pk_fma_f32 v[44:45], v[44:45], v[12:13], v[48:49] op_sel_hi:[1,0,1]
	v_pk_fma_f32 v[48:49], v[52:53], v[12:13], v[56:57] op_sel_hi:[1,0,1]
	v_pk_fma_f32 v[52:53], v[54:55], v[12:13], v[58:59] op_sel_hi:[1,0,1]
	v_pk_fma_f32 v[28:29], v[42:43], v[12:13], v[28:29] op_sel_hi:[1,0,1]
	v_cvt_pk_f32_fp8_e32 v[42:43], v36
	v_cvt_pk_f32_fp8_sdwa v[54:55], v36 src0_sel:WORD_1
	v_cvt_pk_f32_fp8_e32 v[56:57], v37
	v_cvt_pk_f32_fp8_sdwa v[36:37], v37 src0_sel:WORD_1
	v_pk_fma_f32 v[30:31], v[42:43], v[12:13], v[30:31] op_sel:[0,1,0]
	v_pk_fma_f32 v[42:43], v[54:55], v[12:13], v[46:47] op_sel:[0,1,0]
	v_pk_fma_f32 v[46:47], v[56:57], v[12:13], v[50:51] op_sel:[0,1,0]
	v_pk_fma_f32 v[36:37], v[36:37], v[12:13], v[40:41] op_sel:[0,1,0]
	v_cvt_pk_f32_fp8_e32 v[40:41], v38
	v_cvt_pk_f32_fp8_sdwa v[50:51], v38 src0_sel:WORD_1
	v_cvt_pk_f32_fp8_e32 v[54:55], v39
	v_cvt_pk_f32_fp8_sdwa v[38:39], v39 src0_sel:WORD_1
	v_pk_fma_f32 v[40:41], v[40:41], v[12:13], v[44:45] op_sel:[0,1,0]
	v_pk_fma_f32 v[44:45], v[50:51], v[12:13], v[48:49] op_sel:[0,1,0]
	v_pk_fma_f32 v[48:49], v[54:55], v[12:13], v[52:53] op_sel:[0,1,0]
	v_pk_fma_f32 v[12:13], v[38:39], v[12:13], v[28:29] op_sel:[0,1,0]
	v_cvt_pk_f32_fp8_e32 v[28:29], v32
	v_cvt_pk_f32_fp8_sdwa v[38:39], v32 src0_sel:WORD_1
	v_cvt_pk_f32_fp8_e32 v[50:51], v33
	v_cvt_pk_f32_fp8_sdwa v[32:33], v33 src0_sel:WORD_1
	v_pk_fma_f32 v[28:29], v[28:29], v[14:15], v[30:31] op_sel_hi:[1,0,1]
	v_pk_fma_f32 v[30:31], v[38:39], v[14:15], v[42:43] op_sel_hi:[1,0,1]
	v_pk_fma_f32 v[38:39], v[50:51], v[14:15], v[46:47] op_sel_hi:[1,0,1]
	v_pk_fma_f32 v[32:33], v[32:33], v[14:15], v[36:37] op_sel_hi:[1,0,1]
	v_cvt_pk_f32_fp8_e32 v[36:37], v34
	v_cvt_pk_f32_fp8_sdwa v[42:43], v34 src0_sel:WORD_1
	v_cvt_pk_f32_fp8_e32 v[46:47], v35
	v_cvt_pk_f32_fp8_sdwa v[34:35], v35 src0_sel:WORD_1
	v_pk_fma_f32 v[36:37], v[36:37], v[14:15], v[40:41] op_sel_hi:[1,0,1]
	v_pk_fma_f32 v[40:41], v[42:43], v[14:15], v[44:45] op_sel_hi:[1,0,1]
	v_pk_fma_f32 v[42:43], v[46:47], v[14:15], v[48:49] op_sel_hi:[1,0,1]
	v_pk_fma_f32 v[12:13], v[34:35], v[14:15], v[12:13] op_sel_hi:[1,0,1]
	v_cvt_pk_f32_fp8_e32 v[34:35], v24
	v_cvt_pk_f32_fp8_sdwa v[44:45], v24 src0_sel:WORD_1
	v_cvt_pk_f32_fp8_e32 v[46:47], v25
	v_cvt_pk_f32_fp8_sdwa v[24:25], v25 src0_sel:WORD_1
	v_pk_fma_f32 v[28:29], v[34:35], v[14:15], v[28:29] op_sel:[0,1,0]
	v_pk_fma_f32 v[30:31], v[44:45], v[14:15], v[30:31] op_sel:[0,1,0]
	v_pk_fma_f32 v[34:35], v[46:47], v[14:15], v[38:39] op_sel:[0,1,0]
	v_pk_fma_f32 v[24:25], v[24:25], v[14:15], v[32:33] op_sel:[0,1,0]
	v_cvt_pk_f32_fp8_e32 v[32:33], v26
	v_cvt_pk_f32_fp8_sdwa v[38:39], v26 src0_sel:WORD_1
	v_cvt_pk_f32_fp8_e32 v[44:45], v27
	v_cvt_pk_f32_fp8_sdwa v[26:27], v27 src0_sel:WORD_1
	v_pk_fma_f32 v[32:33], v[32:33], v[14:15], v[36:37] op_sel:[0,1,0]
	v_pk_fma_f32 v[36:37], v[38:39], v[14:15], v[40:41] op_sel:[0,1,0]
	v_pk_fma_f32 v[38:39], v[44:45], v[14:15], v[42:43] op_sel:[0,1,0]
	v_pk_fma_f32 v[12:13], v[26:27], v[14:15], v[12:13] op_sel:[0,1,0]
	v_cvt_pk_f32_fp8_e32 v[14:15], v20
	v_cvt_pk_f32_fp8_sdwa v[26:27], v20 src0_sel:WORD_1
	v_cvt_pk_f32_fp8_e32 v[40:41], v21
	v_cvt_pk_f32_fp8_sdwa v[20:21], v21 src0_sel:WORD_1
	v_pk_fma_f32 v[14:15], v[14:15], v[0:1], v[28:29] op_sel_hi:[1,0,1]
	v_pk_fma_f32 v[26:27], v[26:27], v[0:1], v[30:31] op_sel_hi:[1,0,1]
	v_pk_fma_f32 v[28:29], v[40:41], v[0:1], v[34:35] op_sel_hi:[1,0,1]
	v_pk_fma_f32 v[20:21], v[20:21], v[0:1], v[24:25] op_sel_hi:[1,0,1]
	v_cvt_pk_f32_fp8_e32 v[24:25], v22
	v_cvt_pk_f32_fp8_sdwa v[30:31], v22 src0_sel:WORD_1
	v_cvt_pk_f32_fp8_e32 v[34:35], v23
	v_cvt_pk_f32_fp8_sdwa v[22:23], v23 src0_sel:WORD_1
	v_pk_fma_f32 v[24:25], v[24:25], v[0:1], v[32:33] op_sel_hi:[1,0,1]
	v_pk_fma_f32 v[30:31], v[30:31], v[0:1], v[36:37] op_sel_hi:[1,0,1]
	v_pk_fma_f32 v[32:33], v[34:35], v[0:1], v[38:39] op_sel_hi:[1,0,1]
	v_pk_fma_f32 v[12:13], v[22:23], v[0:1], v[12:13] op_sel_hi:[1,0,1]
	v_cvt_pk_f32_fp8_e32 v[22:23], v16
	v_cvt_pk_f32_fp8_sdwa v[34:35], v16 src0_sel:WORD_1
	v_cvt_pk_f32_fp8_e32 v[36:37], v17
	v_cvt_pk_f32_fp8_sdwa v[16:17], v17 src0_sel:WORD_1
	v_pk_fma_f32 v[14:15], v[22:23], v[0:1], v[14:15] op_sel:[0,1,0]
	v_pk_fma_f32 v[22:23], v[34:35], v[0:1], v[26:27] op_sel:[0,1,0]
	v_pk_fma_f32 v[26:27], v[36:37], v[0:1], v[28:29] op_sel:[0,1,0]
	v_pk_fma_f32 v[16:17], v[16:17], v[0:1], v[20:21] op_sel:[0,1,0]
	v_cvt_pk_f32_fp8_e32 v[20:21], v18
	v_cvt_pk_f32_fp8_sdwa v[28:29], v18 src0_sel:WORD_1
	v_cvt_pk_f32_fp8_e32 v[34:35], v19
	v_ashrrev_i32_e32 v205, 31, v204
	v_pk_fma_f32 v[20:21], v[20:21], v[0:1], v[24:25] op_sel:[0,1,0]
	v_pk_fma_f32 v[24:25], v[28:29], v[0:1], v[30:31] op_sel:[0,1,0]
	v_pk_fma_f32 v[28:29], v[34:35], v[0:1], v[32:33] op_sel:[0,1,0]
	v_lshlrev_b64 v[32:33], 12, v[204:205]
	v_lshl_add_u64 v[32:33], v[202:203], 0, v[32:33]
	global_load_dwordx2 v[34:35], v[32:33], off
	v_cvt_pk_f32_fp8_sdwa v[18:19], v19 src0_sel:WORD_1
	v_cvt_pk_f32_fp8_e32 v[30:31], v9
; DI void peer_v_phase(const Params& p) {
;     ...
;     float r8[8], r4[4], r2[2];
; #pragma unroll
;     for (int k = 0; k < 8; ++k) {
;       const float keep = (lane & 32) ? o[k + 8] : o[k], send = (lane & 32) ? o[k] : o[k + 8];
;       r8[k] = keep + __shfl_xor(send, 32);
;     }
; #pragma unroll
;     for (int k = 0; k < 4; ++k) {
;       const float keep = (lane & 16) ? r8[k + 4] : r8[k], send = (lane & 16) ? r8[k] : r8[k + 4];
;       r4[k] = keep + __shfl_xor(send, 16);
;     }
; #pragma unroll
;     for (int k = 0; k < 2; ++k) {
;       const float keep = (lane & 8) ? r4[k + 2] : r4[k], send = (lane & 8) ? r4[k] : r4[k + 2];
;       r2[k] = keep + __shfl_xor(send, 8);
;     }
;     float* xr = p.out + (size_t)tok * 1024 + 128 * g + 16 * s + 2 * q;
;     float2 y = *(const float2*)xr;
;     y.x += r2[0]; y.y += r2[1];
;     *(float2*)xr = y;
;     const float ss = wave_sum(y.x * y.x + y.y * y.y);
;     if (lane == 0) SSP[tok] = ss;
;   };
;   int ea[16], eb[16];
;   PeerVRows ga, gb;
;   peer_load_e(ea, EID, tokof(0), q);
;   peer_load_e(eb, EID, tokof(1), q);
;   gather(ga, ea, tokof(0));
;   for (int k = 0; k < n; k += 2) {
;     peer_load_e(ea, EID, tokof(k + 2), q);
;     gather(gb, eb, tokof(k + 1));
;     __builtin_amdgcn_sched_barrier(0);
;     compute(ga, tokof(k));
;     __builtin_amdgcn_sched_barrier(0);
;     peer_load_e(eb, EID, tokof(k + 3), q);
;     gather(ga, ea, tokof(k + 2));
;     __builtin_amdgcn_sched_barrier(0);
;     if (k + 1 < n) compute(gb, tokof(k + 1));
	v_pk_fma_f32 v[0:1], v[18:19], v[0:1], v[12:13] op_sel:[0,1,0]
	v_cvt_pk_f32_fp8_e32 v[12:13], v8
	v_cvt_pk_f32_fp8_sdwa v[18:19], v8 src0_sel:WORD_1
	v_cvt_pk_f32_fp8_sdwa v[8:9], v9 src0_sel:WORD_1
	v_pk_fma_f32 v[12:13], v[12:13], v[2:3], v[14:15] op_sel_hi:[1,0,1]
	v_pk_fma_f32 v[14:15], v[18:19], v[2:3], v[22:23] op_sel_hi:[1,0,1]
	v_pk_fma_f32 v[18:19], v[30:31], v[2:3], v[26:27] op_sel_hi:[1,0,1]
	v_pk_fma_f32 v[8:9], v[8:9], v[2:3], v[16:17] op_sel_hi:[1,0,1]
	v_cvt_pk_f32_fp8_e32 v[16:17], v10
	v_cvt_pk_f32_fp8_sdwa v[22:23], v10 src0_sel:WORD_1
	v_cvt_pk_f32_fp8_e32 v[26:27], v11
	v_cvt_pk_f32_fp8_sdwa v[10:11], v11 src0_sel:WORD_1
	v_pk_fma_f32 v[16:17], v[16:17], v[2:3], v[20:21] op_sel_hi:[1,0,1]
	v_pk_fma_f32 v[20:21], v[22:23], v[2:3], v[24:25] op_sel_hi:[1,0,1]
	v_pk_fma_f32 v[22:23], v[26:27], v[2:3], v[28:29] op_sel_hi:[1,0,1]
	v_pk_fma_f32 v[0:1], v[10:11], v[2:3], v[0:1] op_sel_hi:[1,0,1]
	v_cvt_pk_f32_fp8_e32 v[10:11], v4
	v_cvt_pk_f32_fp8_sdwa v[24:25], v4 src0_sel:WORD_1
	v_cvt_pk_f32_fp8_e32 v[26:27], v5
	v_cvt_pk_f32_fp8_sdwa v[4:5], v5 src0_sel:WORD_1
	v_pk_fma_f32 v[10:11], v[10:11], v[2:3], v[12:13] op_sel:[0,1,0]
	v_pk_fma_f32 v[12:13], v[24:25], v[2:3], v[14:15] op_sel:[0,1,0]
	v_pk_fma_f32 v[14:15], v[26:27], v[2:3], v[18:19] op_sel:[0,1,0]
	v_pk_fma_f32 v[4:5], v[4:5], v[2:3], v[8:9] op_sel:[0,1,0]
	v_cvt_pk_f32_fp8_e32 v[8:9], v6
	v_cvt_pk_f32_fp8_sdwa v[18:19], v6 src0_sel:WORD_1
	v_cvt_pk_f32_fp8_e32 v[24:25], v7
	v_cvt_pk_f32_fp8_sdwa v[6:7], v7 src0_sel:WORD_1
	v_pk_fma_f32 v[8:9], v[8:9], v[2:3], v[16:17] op_sel:[0,1,0]
	v_pk_fma_f32 v[16:17], v[18:19], v[2:3], v[20:21] op_sel:[0,1,0]
	v_pk_fma_f32 v[18:19], v[24:25], v[2:3], v[22:23] op_sel:[0,1,0]
	v_pk_fma_f32 v[0:1], v[6:7], v[2:3], v[0:1] op_sel:[0,1,0]
	s_nop 1
	v_permlane32_swap_b32 v10, v8
	v_permlane32_swap_b32 v11, v9
	v_pk_add_f32 v[2:3], v[10:11], v[8:9]
	v_permlane32_swap_b32 v12, v16
	v_permlane32_swap_b32 v13, v17
	v_pk_add_f32 v[6:7], v[12:13], v[16:17]
	v_permlane32_swap_b32 v14, v18
	v_permlane32_swap_b32 v15, v19
	v_pk_add_f32 v[8:9], v[14:15], v[18:19]
	v_permlane32_swap_b32 v4, v0
	v_permlane32_swap_b32 v5, v1
	v_pk_add_f32 v[0:1], v[4:5], v[0:1]
	s_nop 1
	v_permlane16_swap_b32 v2, v8
	v_permlane16_swap_b32 v3, v9
	v_pk_add_f32 v[2:3], v[2:3], v[8:9]
	v_permlane16_swap_b32 v6, v0
	v_permlane16_swap_b32 v7, v1
	v_pk_add_f32 v[0:1], v[6:7], v[0:1]
	s_nop 1
	v_add_f32_dpp v4, v2, v2 row_ror:8 row_mask:0xf bank_mask:0x3
	v_add_f32_dpp v5, v3, v3 row_ror:8 row_mask:0xf bank_mask:0x3
	v_add_f32_dpp v4, v0, v0 row_ror:8 row_mask:0xf bank_mask:0xc
	v_add_f32_dpp v5, v1, v1 row_ror:8 row_mask:0xf bank_mask:0xc
	s_waitcnt vmcnt(0)
	v_pk_add_f32 v[2:3], v[4:5], v[34:35]
	global_store_dwordx2 v[32:33], v[2:3], off
	v_pk_mul_f32 v[0:1], v[2:3], v[2:3]
	s_nop 0
	v_add_f32_e32 v0, v0, v1
	s_nop 1
	v_add_f32_dpp v0, v0, v0 quad_perm:[1,0,3,2] row_mask:0xf bank_mask:0xf
	s_nop 1
	v_add_f32_dpp v0, v0, v0 quad_perm:[2,3,0,1] row_mask:0xf bank_mask:0xf
	s_nop 1
	v_add_f32_dpp v0, v0, v0 row_half_mirror row_mask:0xf bank_mask:0xf
	s_nop 1
	v_add_f32_dpp v0, v0, v0 row_mirror row_mask:0xf bank_mask:0xf
	s_nop 1
	v_add_f32_dpp v0, v0, v0 row_bcast:15 row_mask:0xa bank_mask:0xf
	s_nop 1
	v_add_f32_dpp v0, v0, v0 row_bcast:31 row_mask:0xc bank_mask:0xf
	s_and_saveexec_b64 s[8:9], s[6:7]
	s_cbranch_execz .LBB0_1479
	v_mov_b32_e32 v2, v0
	v_lshl_add_u64 v[0:1], v[204:205], 2, s[12:13]
	global_store_dword v[0:1], v2, off
.LBB0_1479:
	s_or_b64 exec, exec, s[8:9]
	v_min_i32_e32 v0, s1, v195
	s_waitcnt lgkmcnt(0)
	v_mad_u64_u32 v[0:1], s[8:9], v0, s18, v[194:195]
	v_ashrrev_i32_e32 v1, 31, v0
	v_lshlrev_b64 v[0:1], 9, v[0:1]
	v_lshl_add_u64 v[0:1], v[198:199], 0, v[0:1]
	global_load_dwordx4 v[96:99], v[0:1], off offset:48
	global_load_dwordx4 v[108:111], v[0:1], off offset:32
	global_load_dwordx4 v[116:119], v[0:1], off offset:16
	global_load_dwordx4 v[132:135], v[0:1], off
	v_ashrrev_i32_e32 v1, 31, v188
	v_mov_b32_e32 v0, v188
	v_ashrrev_i32_e32 v3, 31, v189
	v_mov_b32_e32 v2, v189
	v_lshlrev_b64 v[0:1], 7, v[0:1]
	v_lshlrev_b64 v[2:3], 7, v[2:3]
	v_lshl_add_u64 v[0:1], v[196:197], 0, v[0:1]
	v_lshl_add_u64 v[2:3], v[196:197], 0, v[2:3]
	global_load_dwordx4 v[88:91], v[0:1], off
	global_load_dwordx4 v[84:87], v[2:3], off
	v_ashrrev_i32_e32 v1, 31, v190
	v_mov_b32_e32 v0, v190
	v_ashrrev_i32_e32 v3, 31, v191
	v_mov_b32_e32 v2, v191
	v_lshlrev_b64 v[0:1], 7, v[0:1]
	v_lshlrev_b64 v[2:3], 7, v[2:3]
	v_lshl_add_u64 v[0:1], v[196:197], 0, v[0:1]
	v_lshl_add_u64 v[2:3], v[196:197], 0, v[2:3]
	global_load_dwordx4 v[80:83], v[0:1], off
	global_load_dwordx4 v[76:79], v[2:3], off
	v_ashrrev_i32_e32 v1, 31, v184
	v_mov_b32_e32 v0, v184
	v_ashrrev_i32_e32 v3, 31, v185
	v_mov_b32_e32 v2, v185
	v_lshlrev_b64 v[0:1], 7, v[0:1]
	v_lshlrev_b64 v[2:3], 7, v[2:3]
	v_lshl_add_u64 v[0:1], v[196:197], 0, v[0:1]
	v_lshl_add_u64 v[2:3], v[196:197], 0, v[2:3]
	global_load_dwordx4 v[64:67], v[0:1], off
	global_load_dwordx4 v[56:59], v[2:3], off
	v_ashrrev_i32_e32 v1, 31, v186
	v_mov_b32_e32 v0, v186
	v_ashrrev_i32_e32 v3, 31, v187
	v_mov_b32_e32 v2, v187
	v_lshlrev_b64 v[0:1], 7, v[0:1]
	v_lshlrev_b64 v[2:3], 7, v[2:3]
	v_lshl_add_u64 v[0:1], v[196:197], 0, v[0:1]
	v_lshl_add_u64 v[2:3], v[196:197], 0, v[2:3]
	global_load_dwordx4 v[48:51], v[0:1], off
	global_load_dwordx4 v[44:47], v[2:3], off
	v_ashrrev_i32_e32 v1, 31, v176
	v_mov_b32_e32 v0, v176
	v_ashrrev_i32_e32 v3, 31, v177
	v_mov_b32_e32 v2, v177
	v_lshlrev_b64 v[0:1], 7, v[0:1]
	v_lshlrev_b64 v[2:3], 7, v[2:3]
	v_lshl_add_u64 v[0:1], v[196:197], 0, v[0:1]
	v_lshl_add_u64 v[2:3], v[196:197], 0, v[2:3]
; DI void peer_v_phase(const Params& p) {
;     ...
;   auto gather = [&](PeerVRows& r, const int* e, int tok) {
; #pragma unroll
;     for (int i = 0; i < 16; ++i) r.v[i] = *(const u32x4*)(Vb + (size_t)e[i] * 128);
;     const float4* wp = (const float4*)(W + (size_t)tok * 128 + 16 * q);
; #pragma unroll
;     for (int j = 0; j < 4; ++j) r.w[j] = wp[j];
;   };
;   auto compute = [&](const PeerVRows& r, int tok) {
;     f32x2 o2[8];
; #pragma unroll
;     for (int k = 0; k < 8; ++k) { o2[k][0] = 0.f; o2[k][1] = 0.f; }
; #pragma unroll
;     for (int i = 0; i < 16; ++i) {
;       const float wi = (i & 3) == 0 ? r.w[i >> 2].x : (i & 3) == 1 ? r.w[i >> 2].y : (i & 3) == 2 ? r.w[i >> 2].z : r.w[i >> 2].w;
;       const f32x2 w2 = {wi, wi};
; #pragma unroll
;       for (int j = 0; j < 4; ++j) {
;         const f32x2 lo = __builtin_amdgcn_cvt_pk_f32_fp8((int)r.v[i][j], false);
;         const f32x2 hi = __builtin_amdgcn_cvt_pk_f32_fp8((int)r.v[i][j], true);
;         o2[2 * j] = __builtin_elementwise_fma(lo, w2, o2[2 * j]);
;         o2[2 * j + 1] = __builtin_elementwise_fma(hi, w2, o2[2 * j + 1]);
;       }
;     }
;     ...
;     peer_load_e(eb, EID, tokof(k + 3), q);
;     gather(ga, ea, tokof(k + 2));
;     __builtin_amdgcn_sched_barrier(0);
;     if (k + 1 < n) compute(gb, tokof(k + 1));
	global_load_dwordx4 v[40:43], v[0:1], off
	global_load_dwordx4 v[36:39], v[2:3], off
	v_ashrrev_i32_e32 v1, 31, v178
	v_mov_b32_e32 v0, v178
	v_ashrrev_i32_e32 v3, 31, v179
	v_mov_b32_e32 v2, v179
	v_lshlrev_b64 v[0:1], 7, v[0:1]
	v_lshlrev_b64 v[2:3], 7, v[2:3]
	v_lshl_add_u64 v[0:1], v[196:197], 0, v[0:1]
	v_lshl_add_u64 v[2:3], v[196:197], 0, v[2:3]
	global_load_dwordx4 v[32:35], v[0:1], off
	global_load_dwordx4 v[24:27], v[2:3], off
	v_ashrrev_i32_e32 v1, 31, v172
	v_mov_b32_e32 v0, v172
	v_ashrrev_i32_e32 v3, 31, v173
	v_mov_b32_e32 v2, v173
	v_lshlrev_b64 v[0:1], 7, v[0:1]
	v_lshlrev_b64 v[2:3], 7, v[2:3]
	v_lshl_add_u64 v[0:1], v[196:197], 0, v[0:1]
	v_lshl_add_u64 v[2:3], v[196:197], 0, v[2:3]
	global_load_dwordx4 v[20:23], v[0:1], off
	global_load_dwordx4 v[16:19], v[2:3], off
	v_ashrrev_i32_e32 v1, 31, v174
	v_mov_b32_e32 v0, v174
	v_ashrrev_i32_e32 v3, 31, v175
	v_mov_b32_e32 v2, v175
	v_lshlrev_b64 v[0:1], 7, v[0:1]
	v_lshlrev_b64 v[2:3], 7, v[2:3]
	v_lshl_add_u64 v[0:1], v[196:197], 0, v[0:1]
	v_lshl_add_u64 v[2:3], v[196:197], 0, v[2:3]
	v_lshl_add_u64 v[52:53], v[200:201], 0, v[208:209]
	global_load_dwordx4 v[8:11], v[0:1], off
	global_load_dwordx4 v[4:7], v[2:3], off
	s_nop 0
	global_load_dwordx4 v[0:3], v[52:53], off offset:48
	global_load_dwordx4 v[12:15], v[52:53], off offset:32
	global_load_dwordx4 v[28:31], v[52:53], off offset:16
	s_nop 0
	global_load_dwordx4 v[52:55], v[52:53], off
	v_cmp_lt_i32_e64 s[8:9], s16, v193
	s_and_saveexec_b64 s[16:17], s[8:9]
	s_cbranch_execz .LBB0_1476
	v_cvt_pk_f32_fp8_e32 v[172:173], v168
	v_cvt_pk_f32_fp8_sdwa v[174:175], v168 src0_sel:WORD_1
	v_cvt_pk_f32_fp8_e32 v[176:177], v169
	v_cvt_pk_f32_fp8_sdwa v[168:169], v169 src0_sel:WORD_1
	v_cvt_pk_f32_fp8_e32 v[188:189], v164
	v_cvt_pk_f32_fp8_sdwa v[190:191], v164 src0_sel:WORD_1
	v_cvt_pk_f32_fp8_e32 v[208:209], v165
	v_cvt_pk_f32_fp8_sdwa v[164:165], v165 src0_sel:WORD_1
	v_pk_fma_f32 v[172:173], v[172:173], v[180:181], 0 op_sel_hi:[1,0,0]
	v_pk_fma_f32 v[174:175], v[174:175], v[180:181], 0 op_sel_hi:[1,0,0]
	v_pk_fma_f32 v[168:169], v[168:169], v[180:181], 0 op_sel_hi:[1,0,0]
	v_cvt_pk_f32_fp8_e32 v[178:179], v170
	v_cvt_pk_f32_fp8_sdwa v[184:185], v170 src0_sel:WORD_1
	v_cvt_pk_f32_fp8_e32 v[186:187], v171
	v_cvt_pk_f32_fp8_sdwa v[170:171], v171 src0_sel:WORD_1
	v_pk_fma_f32 v[172:173], v[188:189], v[180:181], v[172:173] op_sel:[0,1,0]
	v_pk_fma_f32 v[174:175], v[190:191], v[180:181], v[174:175] op_sel:[0,1,0]
	v_pk_fma_f32 v[164:165], v[164:165], v[180:181], v[168:169] op_sel:[0,1,0]
	v_cvt_pk_f32_fp8_e32 v[168:169], v166
	v_cvt_pk_f32_fp8_sdwa v[188:189], v166 src0_sel:WORD_1
	v_cvt_pk_f32_fp8_e32 v[190:191], v167
	v_cvt_pk_f32_fp8_sdwa v[166:167], v167 src0_sel:WORD_1
	v_pk_fma_f32 v[176:177], v[176:177], v[180:181], 0 op_sel_hi:[1,0,0]
	v_pk_fma_f32 v[178:179], v[178:179], v[180:181], 0 op_sel_hi:[1,0,0]
	v_pk_fma_f32 v[184:185], v[184:185], v[180:181], 0 op_sel_hi:[1,0,0]
	v_pk_fma_f32 v[186:187], v[186:187], v[180:181], 0 op_sel_hi:[1,0,0]
	v_pk_fma_f32 v[170:171], v[170:171], v[180:181], 0 op_sel_hi:[1,0,0]
	v_pk_fma_f32 v[176:177], v[208:209], v[180:181], v[176:177] op_sel:[0,1,0]
	v_pk_fma_f32 v[168:169], v[168:169], v[180:181], v[178:179] op_sel:[0,1,0]
	v_pk_fma_f32 v[178:179], v[188:189], v[180:181], v[184:185] op_sel:[0,1,0]
	v_pk_fma_f32 v[184:185], v[190:191], v[180:181], v[186:187] op_sel:[0,1,0]
	v_pk_fma_f32 v[166:167], v[166:167], v[180:181], v[170:171] op_sel:[0,1,0]
	v_cvt_pk_f32_fp8_e32 v[170:171], v160
	v_cvt_pk_f32_fp8_sdwa v[180:181], v160 src0_sel:WORD_1
	v_cvt_pk_f32_fp8_e32 v[186:187], v161
	v_cvt_pk_f32_fp8_sdwa v[160:161], v161 src0_sel:WORD_1
	v_pk_fma_f32 v[170:171], v[170:171], v[182:183], v[172:173] op_sel_hi:[1,0,1]
	v_pk_fma_f32 v[172:173], v[180:181], v[182:183], v[174:175] op_sel_hi:[1,0,1]
	v_pk_fma_f32 v[174:175], v[186:187], v[182:183], v[176:177] op_sel_hi:[1,0,1]
	v_pk_fma_f32 v[160:161], v[160:161], v[182:183], v[164:165] op_sel_hi:[1,0,1]
	v_cvt_pk_f32_fp8_e32 v[164:165], v162
	v_cvt_pk_f32_fp8_sdwa v[176:177], v162 src0_sel:WORD_1
	v_cvt_pk_f32_fp8_e32 v[180:181], v163
	v_cvt_pk_f32_fp8_sdwa v[162:163], v163 src0_sel:WORD_1
	v_pk_fma_f32 v[164:165], v[164:165], v[182:183], v[168:169] op_sel_hi:[1,0,1]
	v_pk_fma_f32 v[168:169], v[176:177], v[182:183], v[178:179] op_sel_hi:[1,0,1]
	v_pk_fma_f32 v[176:177], v[180:181], v[182:183], v[184:185] op_sel_hi:[1,0,1]
	v_pk_fma_f32 v[162:163], v[162:163], v[182:183], v[166:167] op_sel_hi:[1,0,1]
	v_mov_b32_e32 v166, v183
	v_cvt_pk_f32_fp8_e32 v[178:179], v152
	v_cvt_pk_f32_fp8_sdwa v[180:181], v152 src0_sel:WORD_1
	v_cvt_pk_f32_fp8_e32 v[182:183], v153
	v_cvt_pk_f32_fp8_sdwa v[152:153], v153 src0_sel:WORD_1
	v_pk_fma_f32 v[170:171], v[178:179], v[166:167], v[170:171] op_sel_hi:[1,0,1]
	v_pk_fma_f32 v[172:173], v[180:181], v[166:167], v[172:173] op_sel_hi:[1,0,1]
	v_cvt_pk_f32_fp8_sdwa v[178:179], v154 src0_sel:WORD_1
	v_pk_fma_f32 v[152:153], v[152:153], v[166:167], v[160:161] op_sel_hi:[1,0,1]
	v_cvt_pk_f32_fp8_e32 v[160:161], v154
	v_cvt_pk_f32_fp8_e32 v[180:181], v155
	v_cvt_pk_f32_fp8_sdwa v[154:155], v155 src0_sel:WORD_1
	v_pk_fma_f32 v[174:175], v[182:183], v[166:167], v[174:175] op_sel_hi:[1,0,1]
	v_pk_fma_f32 v[160:161], v[160:161], v[166:167], v[164:165] op_sel_hi:[1,0,1]
	v_pk_fma_f32 v[164:165], v[178:179], v[166:167], v[168:169] op_sel_hi:[1,0,1]
	v_pk_fma_f32 v[168:169], v[180:181], v[166:167], v[176:177] op_sel_hi:[1,0,1]
	v_pk_fma_f32 v[154:155], v[154:155], v[166:167], v[162:163] op_sel_hi:[1,0,1]
	v_cvt_pk_f32_fp8_e32 v[162:163], v148
	v_cvt_pk_f32_fp8_sdwa v[166:167], v148 src0_sel:WORD_1
	v_cvt_pk_f32_fp8_e32 v[176:177], v149
; DI void peer_v_phase(const Params& p) {
;     ...
; #pragma unroll
;     for (int i = 0; i < 16; ++i) {
;       const float wi = (i & 3) == 0 ? r.w[i >> 2].x : (i & 3) == 1 ? r.w[i >> 2].y : (i & 3) == 2 ? r.w[i >> 2].z : r.w[i >> 2].w;
;       const f32x2 w2 = {wi, wi};
; #pragma unroll
;       for (int j = 0; j < 4; ++j) {
;         const f32x2 lo = __builtin_amdgcn_cvt_pk_f32_fp8((int)r.v[i][j], false);
;         const f32x2 hi = __builtin_amdgcn_cvt_pk_f32_fp8((int)r.v[i][j], true);
;         o2[2 * j] = __builtin_elementwise_fma(lo, w2, o2[2 * j]);
;         o2[2 * j + 1] = __builtin_elementwise_fma(hi, w2, o2[2 * j + 1]);
;       }
;     }
	v_cvt_pk_f32_fp8_sdwa v[148:149], v149 src0_sel:WORD_1
	v_pk_fma_f32 v[162:163], v[162:163], v[156:157], v[170:171] op_sel_hi:[1,0,1]
	v_pk_fma_f32 v[166:167], v[166:167], v[156:157], v[172:173] op_sel_hi:[1,0,1]
	v_pk_fma_f32 v[170:171], v[176:177], v[156:157], v[174:175] op_sel_hi:[1,0,1]
	v_pk_fma_f32 v[148:149], v[148:149], v[156:157], v[152:153] op_sel_hi:[1,0,1]
	v_cvt_pk_f32_fp8_e32 v[152:153], v150
	v_cvt_pk_f32_fp8_sdwa v[172:173], v150 src0_sel:WORD_1
	v_cvt_pk_f32_fp8_e32 v[174:175], v151
	v_cvt_pk_f32_fp8_sdwa v[150:151], v151 src0_sel:WORD_1
	v_pk_fma_f32 v[152:153], v[152:153], v[156:157], v[160:161] op_sel_hi:[1,0,1]
	v_pk_fma_f32 v[160:161], v[172:173], v[156:157], v[164:165] op_sel_hi:[1,0,1]
	v_pk_fma_f32 v[164:165], v[174:175], v[156:157], v[168:169] op_sel_hi:[1,0,1]
	v_pk_fma_f32 v[150:151], v[150:151], v[156:157], v[154:155] op_sel_hi:[1,0,1]
	v_mov_b32_e32 v154, v157
	v_cvt_pk_f32_fp8_e32 v[156:157], v144
	v_cvt_pk_f32_fp8_sdwa v[168:169], v144 src0_sel:WORD_1
	v_cvt_pk_f32_fp8_e32 v[172:173], v145
	v_cvt_pk_f32_fp8_sdwa v[144:145], v145 src0_sel:WORD_1
	v_pk_fma_f32 v[156:157], v[156:157], v[154:155], v[162:163] op_sel_hi:[1,0,1]
	v_pk_fma_f32 v[162:163], v[168:169], v[154:155], v[166:167] op_sel_hi:[1,0,1]
	v_pk_fma_f32 v[166:167], v[172:173], v[154:155], v[170:171] op_sel_hi:[1,0,1]
	v_pk_fma_f32 v[144:145], v[144:145], v[154:155], v[148:149] op_sel_hi:[1,0,1]
	v_cvt_pk_f32_fp8_e32 v[148:149], v146
	v_cvt_pk_f32_fp8_sdwa v[168:169], v146 src0_sel:WORD_1
	v_cvt_pk_f32_fp8_e32 v[170:171], v147
	v_cvt_pk_f32_fp8_sdwa v[146:147], v147 src0_sel:WORD_1
	v_pk_fma_f32 v[148:149], v[148:149], v[154:155], v[152:153] op_sel_hi:[1,0,1]
	v_pk_fma_f32 v[152:153], v[168:169], v[154:155], v[160:161] op_sel_hi:[1,0,1]
	v_pk_fma_f32 v[160:161], v[170:171], v[154:155], v[164:165] op_sel_hi:[1,0,1]
	v_pk_fma_f32 v[146:147], v[146:147], v[154:155], v[150:151] op_sel_hi:[1,0,1]
	v_cvt_pk_f32_fp8_e32 v[150:151], v140
	v_cvt_pk_f32_fp8_sdwa v[154:155], v140 src0_sel:WORD_1
	v_cvt_pk_f32_fp8_e32 v[164:165], v141
	v_cvt_pk_f32_fp8_sdwa v[140:141], v141 src0_sel:WORD_1
	v_pk_fma_f32 v[150:151], v[150:151], v[158:159], v[156:157] op_sel_hi:[1,0,1]
	v_pk_fma_f32 v[154:155], v[154:155], v[158:159], v[162:163] op_sel_hi:[1,0,1]
	v_pk_fma_f32 v[156:157], v[164:165], v[158:159], v[166:167] op_sel_hi:[1,0,1]
	v_pk_fma_f32 v[140:141], v[140:141], v[158:159], v[144:145] op_sel_hi:[1,0,1]
	v_cvt_pk_f32_fp8_e32 v[144:145], v142
	v_cvt_pk_f32_fp8_sdwa v[162:163], v142 src0_sel:WORD_1
	v_cvt_pk_f32_fp8_e32 v[164:165], v143
	v_cvt_pk_f32_fp8_sdwa v[142:143], v143 src0_sel:WORD_1
	v_pk_fma_f32 v[144:145], v[144:145], v[158:159], v[148:149] op_sel_hi:[1,0,1]
	v_pk_fma_f32 v[148:149], v[162:163], v[158:159], v[152:153] op_sel_hi:[1,0,1]
	v_pk_fma_f32 v[152:153], v[164:165], v[158:159], v[160:161] op_sel_hi:[1,0,1]
	v_pk_fma_f32 v[142:143], v[142:143], v[158:159], v[146:147] op_sel_hi:[1,0,1]
	v_mov_b32_e32 v146, v159
	v_cvt_pk_f32_fp8_e32 v[158:159], v136
	v_cvt_pk_f32_fp8_sdwa v[160:161], v136 src0_sel:WORD_1
	v_cvt_pk_f32_fp8_e32 v[162:163], v137
	v_cvt_pk_f32_fp8_sdwa v[136:137], v137 src0_sel:WORD_1
	v_pk_fma_f32 v[150:151], v[158:159], v[146:147], v[150:151] op_sel_hi:[1,0,1]
	v_pk_fma_f32 v[154:155], v[160:161], v[146:147], v[154:155] op_sel_hi:[1,0,1]
	v_cvt_pk_f32_fp8_sdwa v[158:159], v138 src0_sel:WORD_1
	v_pk_fma_f32 v[136:137], v[136:137], v[146:147], v[140:141] op_sel_hi:[1,0,1]
	v_cvt_pk_f32_fp8_e32 v[140:141], v138
	v_cvt_pk_f32_fp8_e32 v[160:161], v139
	v_cvt_pk_f32_fp8_sdwa v[138:139], v139 src0_sel:WORD_1
	v_pk_fma_f32 v[156:157], v[162:163], v[146:147], v[156:157] op_sel_hi:[1,0,1]
	v_pk_fma_f32 v[140:141], v[140:141], v[146:147], v[144:145] op_sel_hi:[1,0,1]
	v_pk_fma_f32 v[144:145], v[158:159], v[146:147], v[148:149] op_sel_hi:[1,0,1]
	v_pk_fma_f32 v[148:149], v[160:161], v[146:147], v[152:153] op_sel_hi:[1,0,1]
	v_pk_fma_f32 v[138:139], v[138:139], v[146:147], v[142:143] op_sel_hi:[1,0,1]
	v_cvt_pk_f32_fp8_e32 v[142:143], v128
	v_cvt_pk_f32_fp8_sdwa v[146:147], v128 src0_sel:WORD_1
	v_cvt_pk_f32_fp8_e32 v[152:153], v129
	v_cvt_pk_f32_fp8_sdwa v[128:129], v129 src0_sel:WORD_1
	v_pk_fma_f32 v[142:143], v[142:143], v[124:125], v[150:151] op_sel_hi:[1,0,1]
	v_pk_fma_f32 v[146:147], v[146:147], v[124:125], v[154:155] op_sel_hi:[1,0,1]
	v_pk_fma_f32 v[150:151], v[152:153], v[124:125], v[156:157] op_sel_hi:[1,0,1]
	v_pk_fma_f32 v[128:129], v[128:129], v[124:125], v[136:137] op_sel_hi:[1,0,1]
	v_cvt_pk_f32_fp8_e32 v[136:137], v130
	v_cvt_pk_f32_fp8_sdwa v[152:153], v130 src0_sel:WORD_1
	v_cvt_pk_f32_fp8_e32 v[154:155], v131
	v_cvt_pk_f32_fp8_sdwa v[130:131], v131 src0_sel:WORD_1
	v_pk_fma_f32 v[136:137], v[136:137], v[124:125], v[140:141] op_sel_hi:[1,0,1]
	v_pk_fma_f32 v[140:141], v[152:153], v[124:125], v[144:145] op_sel_hi:[1,0,1]
	v_pk_fma_f32 v[144:145], v[154:155], v[124:125], v[148:149] op_sel_hi:[1,0,1]
	v_pk_fma_f32 v[130:131], v[130:131], v[124:125], v[138:139] op_sel_hi:[1,0,1]
	v_cvt_pk_f32_fp8_e32 v[138:139], v120
	v_cvt_pk_f32_fp8_sdwa v[148:149], v120 src0_sel:WORD_1
	v_cvt_pk_f32_fp8_e32 v[152:153], v121
	v_cvt_pk_f32_fp8_sdwa v[120:121], v121 src0_sel:WORD_1
	v_mov_b32_e32 v124, v125
	v_pk_fma_f32 v[138:139], v[138:139], v[124:125], v[142:143] op_sel_hi:[1,0,1]
	v_pk_fma_f32 v[142:143], v[148:149], v[124:125], v[146:147] op_sel_hi:[1,0,1]
	v_pk_fma_f32 v[146:147], v[152:153], v[124:125], v[150:151] op_sel_hi:[1,0,1]
	v_pk_fma_f32 v[120:121], v[120:121], v[124:125], v[128:129] op_sel_hi:[1,0,1]
	v_cvt_pk_f32_fp8_e32 v[128:129], v122
	v_cvt_pk_f32_fp8_sdwa v[148:149], v122 src0_sel:WORD_1
	v_cvt_pk_f32_fp8_e32 v[150:151], v123
; DI void peer_v_phase(const Params& p) {
;     ...
; #pragma unroll
;     for (int i = 0; i < 16; ++i) {
;       const float wi = (i & 3) == 0 ? r.w[i >> 2].x : (i & 3) == 1 ? r.w[i >> 2].y : (i & 3) == 2 ? r.w[i >> 2].z : r.w[i >> 2].w;
;       const f32x2 w2 = {wi, wi};
; #pragma unroll
;       for (int j = 0; j < 4; ++j) {
;         const f32x2 lo = __builtin_amdgcn_cvt_pk_f32_fp8((int)r.v[i][j], false);
;         const f32x2 hi = __builtin_amdgcn_cvt_pk_f32_fp8((int)r.v[i][j], true);
;         o2[2 * j] = __builtin_elementwise_fma(lo, w2, o2[2 * j]);
;         o2[2 * j + 1] = __builtin_elementwise_fma(hi, w2, o2[2 * j + 1]);
;       }
;     }
	v_cvt_pk_f32_fp8_sdwa v[122:123], v123 src0_sel:WORD_1
	v_pk_fma_f32 v[128:129], v[128:129], v[124:125], v[136:137] op_sel_hi:[1,0,1]
	v_pk_fma_f32 v[136:137], v[148:149], v[124:125], v[140:141] op_sel_hi:[1,0,1]
	v_pk_fma_f32 v[140:141], v[150:151], v[124:125], v[144:145] op_sel_hi:[1,0,1]
	v_pk_fma_f32 v[122:123], v[122:123], v[124:125], v[130:131] op_sel_hi:[1,0,1]
	v_cvt_pk_f32_fp8_e32 v[124:125], v112
	v_cvt_pk_f32_fp8_sdwa v[130:131], v112 src0_sel:WORD_1
	v_cvt_pk_f32_fp8_e32 v[144:145], v113
	v_cvt_pk_f32_fp8_sdwa v[112:113], v113 src0_sel:WORD_1
	v_pk_fma_f32 v[124:125], v[124:125], v[126:127], v[138:139] op_sel_hi:[1,0,1]
	v_pk_fma_f32 v[130:131], v[130:131], v[126:127], v[142:143] op_sel_hi:[1,0,1]
	v_pk_fma_f32 v[138:139], v[144:145], v[126:127], v[146:147] op_sel_hi:[1,0,1]
	v_pk_fma_f32 v[112:113], v[112:113], v[126:127], v[120:121] op_sel_hi:[1,0,1]
	v_cvt_pk_f32_fp8_e32 v[120:121], v114
	v_cvt_pk_f32_fp8_sdwa v[142:143], v114 src0_sel:WORD_1
	v_cvt_pk_f32_fp8_e32 v[144:145], v115
	v_cvt_pk_f32_fp8_sdwa v[114:115], v115 src0_sel:WORD_1
	v_pk_fma_f32 v[120:121], v[120:121], v[126:127], v[128:129] op_sel_hi:[1,0,1]
	v_pk_fma_f32 v[128:129], v[142:143], v[126:127], v[136:137] op_sel_hi:[1,0,1]
	v_pk_fma_f32 v[136:137], v[144:145], v[126:127], v[140:141] op_sel_hi:[1,0,1]
	v_pk_fma_f32 v[114:115], v[114:115], v[126:127], v[122:123] op_sel_hi:[1,0,1]
	v_cvt_pk_f32_fp8_e32 v[122:123], v104
	v_cvt_pk_f32_fp8_sdwa v[140:141], v104 src0_sel:WORD_1
	v_cvt_pk_f32_fp8_e32 v[142:143], v105
	v_cvt_pk_f32_fp8_sdwa v[104:105], v105 src0_sel:WORD_1
	v_mov_b32_e32 v126, v127
	v_pk_fma_f32 v[122:123], v[122:123], v[126:127], v[124:125] op_sel_hi:[1,0,1]
	v_pk_fma_f32 v[124:125], v[140:141], v[126:127], v[130:131] op_sel_hi:[1,0,1]
	v_pk_fma_f32 v[130:131], v[142:143], v[126:127], v[138:139] op_sel_hi:[1,0,1]
	v_cvt_pk_f32_fp8_e32 v[138:139], v106
	v_pk_fma_f32 v[104:105], v[104:105], v[126:127], v[112:113] op_sel_hi:[1,0,1]
	v_cvt_pk_f32_fp8_sdwa v[112:113], v106 src0_sel:WORD_1
	v_cvt_pk_f32_fp8_e32 v[140:141], v107
	v_cvt_pk_f32_fp8_sdwa v[106:107], v107 src0_sel:WORD_1
	v_pk_fma_f32 v[120:121], v[138:139], v[126:127], v[120:121] op_sel_hi:[1,0,1]
	v_pk_fma_f32 v[112:113], v[112:113], v[126:127], v[128:129] op_sel_hi:[1,0,1]
	v_pk_fma_f32 v[128:129], v[140:141], v[126:127], v[136:137] op_sel_hi:[1,0,1]
	v_pk_fma_f32 v[106:107], v[106:107], v[126:127], v[114:115] op_sel_hi:[1,0,1]
	v_cvt_pk_f32_fp8_sdwa v[114:115], v100 src0_sel:WORD_1
	v_cvt_pk_f32_fp8_e32 v[126:127], v101
	v_cvt_pk_f32_fp8_e32 v[136:137], v100
	v_cvt_pk_f32_fp8_sdwa v[100:101], v101 src0_sel:WORD_1
	v_pk_fma_f32 v[114:115], v[114:115], v[72:73], v[124:125] op_sel_hi:[1,0,1]
	v_pk_fma_f32 v[124:125], v[126:127], v[72:73], v[130:131] op_sel_hi:[1,0,1]
	v_cvt_pk_f32_fp8_e32 v[126:127], v102
	v_pk_fma_f32 v[100:101], v[100:101], v[72:73], v[104:105] op_sel_hi:[1,0,1]
	v_cvt_pk_f32_fp8_sdwa v[104:105], v102 src0_sel:WORD_1
	v_cvt_pk_f32_fp8_e32 v[130:131], v103
	v_cvt_pk_f32_fp8_sdwa v[102:103], v103 src0_sel:WORD_1
	v_pk_fma_f32 v[120:121], v[126:127], v[72:73], v[120:121] op_sel_hi:[1,0,1]
	v_cvt_pk_f32_fp8_e32 v[126:127], v92
	v_pk_fma_f32 v[122:123], v[136:137], v[72:73], v[122:123] op_sel_hi:[1,0,1]
	v_pk_fma_f32 v[102:103], v[102:103], v[72:73], v[106:107] op_sel_hi:[1,0,1]
	v_cvt_pk_f32_fp8_sdwa v[106:107], v92 src0_sel:WORD_1
	v_pk_fma_f32 v[104:105], v[104:105], v[72:73], v[112:113] op_sel_hi:[1,0,1]
	v_pk_fma_f32 v[112:113], v[130:131], v[72:73], v[128:129] op_sel_hi:[1,0,1]
	v_mov_b32_e32 v72, v73
	v_pk_fma_f32 v[122:123], v[126:127], v[72:73], v[122:123] op_sel_hi:[1,0,1]
	v_cvt_pk_f32_fp8_e32 v[126:127], v93
	v_cvt_pk_f32_fp8_sdwa v[92:93], v93 src0_sel:WORD_1
	v_pk_fma_f32 v[106:107], v[106:107], v[72:73], v[114:115] op_sel_hi:[1,0,1]
	v_cvt_pk_f32_fp8_e32 v[114:115], v94
	v_pk_fma_f32 v[124:125], v[126:127], v[72:73], v[124:125] op_sel_hi:[1,0,1]
	v_pk_fma_f32 v[92:93], v[92:93], v[72:73], v[100:101] op_sel_hi:[1,0,1]
	v_cvt_pk_f32_fp8_sdwa v[100:101], v94 src0_sel:WORD_1
	v_pk_fma_f32 v[114:115], v[114:115], v[72:73], v[120:121] op_sel_hi:[1,0,1]
	v_cvt_pk_f32_fp8_e32 v[120:121], v95
; DI void peer_v_phase(const Params& p) {
;     ...
; #pragma unroll
;     for (int i = 0; i < 16; ++i) {
;       const float wi = (i & 3) == 0 ? r.w[i >> 2].x : (i & 3) == 1 ? r.w[i >> 2].y : (i & 3) == 2 ? r.w[i >> 2].z : r.w[i >> 2].w;
;       const f32x2 w2 = {wi, wi};
; #pragma unroll
;       for (int j = 0; j < 4; ++j) {
;         const f32x2 lo = __builtin_amdgcn_cvt_pk_f32_fp8((int)r.v[i][j], false);
;         const f32x2 hi = __builtin_amdgcn_cvt_pk_f32_fp8((int)r.v[i][j], true);
;         o2[2 * j] = __builtin_elementwise_fma(lo, w2, o2[2 * j]);
;         o2[2 * j + 1] = __builtin_elementwise_fma(hi, w2, o2[2 * j + 1]);
;       }
;     }
;     float o[16];
; #pragma unroll
;     for (int k = 0; k < 8; ++k) { o[2 * k] = o2[k][0]; o[2 * k + 1] = o2[k][1]; }
;     float r8[8], r4[4], r2[2];
; #pragma unroll
;     for (int k = 0; k < 8; ++k) {
;       const float keep = (lane & 32) ? o[k + 8] : o[k], send = (lane & 32) ? o[k] : o[k + 8];
;       r8[k] = keep + __shfl_xor(send, 32);
;     }
; #pragma unroll
;     for (int k = 0; k < 4; ++k) {
;       const float keep = (lane & 16) ? r8[k + 4] : r8[k], send = (lane & 16) ? r8[k] : r8[k + 4];
;       r4[k] = keep + __shfl_xor(send, 16);
;     }
; #pragma unroll
;     for (int k = 0; k < 2; ++k) {
;       const float keep = (lane & 8) ? r4[k + 2] : r4[k], send = (lane & 8) ? r4[k] : r4[k + 2];
;       r2[k] = keep + __shfl_xor(send, 8);
;     }
;     float* xr = p.out + (size_t)tok * 1024 + 128 * g + 16 * s + 2 * q;
;     float2 y = *(const float2*)xr;
;     y.x += r2[0]; y.y += r2[1];
;     *(float2*)xr = y;
;     const float ss = wave_sum(y.x * y.x + y.y * y.y);
;     if (lane == 0) SSP[tok] = ss;
	v_cvt_pk_f32_fp8_sdwa v[94:95], v95 src0_sel:WORD_1
	v_pk_fma_f32 v[100:101], v[100:101], v[72:73], v[104:105] op_sel_hi:[1,0,1]
	v_cvt_pk_f32_fp8_e32 v[104:105], v68
	v_pk_fma_f32 v[112:113], v[120:121], v[72:73], v[112:113] op_sel_hi:[1,0,1]
	v_lshlrev_b64 v[120:121], 12, v[206:207]
	v_lshl_add_u64 v[120:121], v[202:203], 0, v[120:121]
	v_pk_fma_f32 v[72:73], v[94:95], v[72:73], v[102:103] op_sel_hi:[1,0,1]
	v_pk_fma_f32 v[102:103], v[104:105], v[74:75], v[122:123] op_sel_hi:[1,0,1]
	global_load_dwordx2 v[122:123], v[120:121], off
	v_cvt_pk_f32_fp8_sdwa v[94:95], v68 src0_sel:WORD_1
	v_cvt_pk_f32_fp8_e32 v[104:105], v69
	v_cvt_pk_f32_fp8_sdwa v[68:69], v69 src0_sel:WORD_1
	v_pk_fma_f32 v[94:95], v[94:95], v[74:75], v[106:107] op_sel_hi:[1,0,1]
	v_pk_fma_f32 v[104:105], v[104:105], v[74:75], v[124:125] op_sel_hi:[1,0,1]
	v_pk_fma_f32 v[68:69], v[68:69], v[74:75], v[92:93] op_sel_hi:[1,0,1]
	v_cvt_pk_f32_fp8_e32 v[92:93], v70
	v_cvt_pk_f32_fp8_sdwa v[106:107], v70 src0_sel:WORD_1
	v_cvt_pk_f32_fp8_e32 v[124:125], v71
	v_cvt_pk_f32_fp8_sdwa v[70:71], v71 src0_sel:WORD_1
	v_pk_fma_f32 v[92:93], v[92:93], v[74:75], v[114:115] op_sel_hi:[1,0,1]
	v_pk_fma_f32 v[100:101], v[106:107], v[74:75], v[100:101] op_sel_hi:[1,0,1]
	v_pk_fma_f32 v[106:107], v[124:125], v[74:75], v[112:113] op_sel_hi:[1,0,1]
	v_pk_fma_f32 v[70:71], v[70:71], v[74:75], v[72:73] op_sel_hi:[1,0,1]
	v_mov_b32_e32 v72, v75
	v_cvt_pk_f32_fp8_e32 v[74:75], v60
	v_cvt_pk_f32_fp8_sdwa v[112:113], v60 src0_sel:WORD_1
	v_cvt_pk_f32_fp8_e32 v[114:115], v61
	v_cvt_pk_f32_fp8_sdwa v[60:61], v61 src0_sel:WORD_1
	v_pk_fma_f32 v[74:75], v[74:75], v[72:73], v[102:103] op_sel_hi:[1,0,1]
	v_pk_fma_f32 v[94:95], v[112:113], v[72:73], v[94:95] op_sel_hi:[1,0,1]
	v_pk_fma_f32 v[102:103], v[114:115], v[72:73], v[104:105] op_sel_hi:[1,0,1]
	v_pk_fma_f32 v[60:61], v[60:61], v[72:73], v[68:69] op_sel_hi:[1,0,1]
	v_cvt_pk_f32_fp8_e32 v[68:69], v62
	v_cvt_pk_f32_fp8_sdwa v[104:105], v62 src0_sel:WORD_1
	v_cvt_pk_f32_fp8_e32 v[112:113], v63
	v_cvt_pk_f32_fp8_sdwa v[62:63], v63 src0_sel:WORD_1
	v_pk_fma_f32 v[68:69], v[68:69], v[72:73], v[92:93] op_sel_hi:[1,0,1]
	v_pk_fma_f32 v[92:93], v[104:105], v[72:73], v[100:101] op_sel_hi:[1,0,1]
	v_pk_fma_f32 v[100:101], v[112:113], v[72:73], v[106:107] op_sel_hi:[1,0,1]
	v_pk_fma_f32 v[62:63], v[62:63], v[72:73], v[70:71] op_sel_hi:[1,0,1]
	s_nop 1
	v_permlane32_swap_b32 v74, v68
	v_permlane32_swap_b32 v75, v69
	v_pk_add_f32 v[68:69], v[74:75], v[68:69]
	v_permlane32_swap_b32 v94, v92
	v_permlane32_swap_b32 v95, v93
	v_pk_add_f32 v[70:71], v[94:95], v[92:93]
	v_permlane32_swap_b32 v102, v100
	v_permlane32_swap_b32 v103, v101
	v_pk_add_f32 v[72:73], v[102:103], v[100:101]
	v_permlane32_swap_b32 v60, v62
	v_permlane32_swap_b32 v61, v63
	v_pk_add_f32 v[60:61], v[60:61], v[62:63]
	s_nop 1
	v_permlane16_swap_b32 v68, v72
	v_permlane16_swap_b32 v69, v73
	v_pk_add_f32 v[62:63], v[68:69], v[72:73]
	v_permlane16_swap_b32 v70, v60
	v_permlane16_swap_b32 v71, v61
	v_pk_add_f32 v[60:61], v[70:71], v[60:61]
	s_nop 1
	v_add_f32_dpp v68, v62, v62 row_ror:8 row_mask:0xf bank_mask:0x3
	v_add_f32_dpp v69, v63, v63 row_ror:8 row_mask:0xf bank_mask:0x3
	v_add_f32_dpp v68, v60, v60 row_ror:8 row_mask:0xf bank_mask:0xc
	v_add_f32_dpp v69, v61, v61 row_ror:8 row_mask:0xf bank_mask:0xc
	s_waitcnt vmcnt(0)
	v_pk_add_f32 v[62:63], v[68:69], v[122:123]
	global_store_dwordx2 v[120:121], v[62:63], off
	v_pk_mul_f32 v[60:61], v[62:63], v[62:63]
	s_nop 0
	v_add_f32_e32 v60, v60, v61
	s_nop 1
	v_add_f32_dpp v60, v60, v60 quad_perm:[1,0,3,2] row_mask:0xf bank_mask:0xf
	s_nop 1
	v_add_f32_dpp v60, v60, v60 quad_perm:[2,3,0,1] row_mask:0xf bank_mask:0xf
	s_nop 1
	v_add_f32_dpp v60, v60, v60 row_half_mirror row_mask:0xf bank_mask:0xf
	s_nop 1
	v_add_f32_dpp v60, v60, v60 row_mirror row_mask:0xf bank_mask:0xf
	s_nop 1
	v_add_f32_dpp v60, v60, v60 row_bcast:15 row_mask:0xa bank_mask:0xf
	s_nop 1
	v_add_f32_dpp v60, v60, v60 row_bcast:31 row_mask:0xc bank_mask:0xf
	s_and_b64 exec, exec, s[6:7]
	s_cbranch_execz .LBB0_1476
	v_mov_b32_e32 v62, v60
	v_lshl_add_u64 v[60:61], v[206:207], 2, s[12:13]
	global_store_dword v[60:61], v62, off
	s_branch .LBB0_1476
